# v23 with 13 of the 16 exps (+11 sums) of the next tile's first score block in the PV phase, the other 3 at the head of the next QK phase
# speedup vs baseline: 1.0119x; 1.0119x over previous
.LBB0_1038:
	s_or_b64 exec, exec, s[4:5]
	v_and_b32_e32 v0, 0x60, v26
	s_movk_i32 s4, 0x90
	v_lshlrev_b32_e32 v2, 3, v32
	v_mad_u32_u24 v207, v203, s4, 0
	v_mad_u64_u32 v[0:1], s[4:5], v28, s4, v[0:1]
	v_and_or_b32 v0, v2, 8, v0
	v_lshlrev_b32_e32 v1, 6, v203
	v_add_u32_e32 v208, 0, v0
	v_add3_u32 v204, v207, v1, v184
	v_add_u32_e32 v1, 0, v4
	v_add_u32_e32 v205, 0x9800, v208
	s_waitcnt vmcnt(3)
	ds_write_b128 v1, v[8:11] offset:13312
	s_waitcnt vmcnt(2)
	ds_write2_b64 v205, v[16:17], v[18:19] offset0:128 offset1:130
	s_waitcnt lgkmcnt(0)
	s_barrier
	ds_read_b128 v[0:3], v204
	ds_read_b128 v[4:7], v204 offset:32
	ds_read_b128 v[8:11], v204 offset:6656
	ds_read_b128 v[12:15], v204 offset:6688
	ds_read_b128 v[16:19], v204 offset:64
	ds_read_b128 v[28:31], v204 offset:96
	ds_read_b128 v[64:67], v204 offset:6720
	ds_read_b128 v[68:71], v204 offset:6752
	ds_read_b128 v[72:75], v204 offset:128
	ds_read_b128 v[76:79], v204 offset:160
	ds_read_b128 v[80:83], v204 offset:6784
	ds_read_b128 v[84:87], v204 offset:6816
	s_mov_b32 s91, 2
	s_lshl_b32 s87, s6, 2
	s_waitcnt lgkmcnt(11)
	v_mfma_f32_32x32x16_bf16 v[48:63], v[0:3], v[100:103], 0
	s_mov_b32 s79, 0
	s_waitcnt lgkmcnt(9)
	v_mfma_f32_32x32x16_bf16 v[32:47], v[8:11], v[100:103], 0
	v_mfma_f32_32x32x16_bf16 v[48:63], v[4:7], v[104:107], v[48:63]
	s_waitcnt lgkmcnt(8)
	v_mfma_f32_32x32x16_bf16 v[32:47], v[12:15], v[104:107], v[32:47]
	s_waitcnt lgkmcnt(7)
	v_mfma_f32_32x32x16_bf16 v[48:63], v[16:19], v[108:111], v[48:63]
	s_waitcnt lgkmcnt(5)
	v_mfma_f32_32x32x16_bf16 v[32:47], v[64:67], v[108:111], v[32:47]
	v_mfma_f32_32x32x16_bf16 v[48:63], v[28:31], v[112:115], v[48:63]
	s_waitcnt lgkmcnt(4)
	v_mfma_f32_32x32x16_bf16 v[32:47], v[68:71], v[112:115], v[32:47]
	s_waitcnt lgkmcnt(3)
	v_mfma_f32_32x32x16_bf16 v[48:63], v[72:75], v[116:119], v[48:63]
	s_waitcnt lgkmcnt(1)
	v_mfma_f32_32x32x16_bf16 v[32:47], v[80:83], v[116:119], v[32:47]
	v_mfma_f32_32x32x16_bf16 v[48:63], v[76:79], v[120:123], v[48:63]
	s_waitcnt lgkmcnt(0)
	v_mfma_f32_32x32x16_bf16 v[32:47], v[84:87], v[120:123], v[32:47]
	ds_read_b128 v[172:175], v204 offset:13312
	ds_read_b128 v[152:155], v204 offset:13344
	ds_read_b128 v[180:183], v204 offset:19968
	ds_read_b128 v[164:167], v204 offset:20000
	ds_read_b128 v[156:159], v204 offset:13376
	ds_read_b128 v[140:143], v204 offset:13408
	ds_read_b128 v[176:179], v204 offset:20032
	ds_read_b128 v[160:163], v204 offset:20064
	ds_read_b128 v[148:151], v204 offset:13440
	ds_read_b128 v[136:139], v204 offset:13472
	ds_read_b128 v[168:171], v204 offset:20096
	ds_read_b128 v[144:147], v204 offset:20128
	s_add_u32 s4, s60, 0x100
	v_lshl_add_u64 v[0:1], s[60:61], 0, v[24:25]
	v_mov_b32_e32 v27, v97
	s_addc_u32 s5, 0, 0
	v_lshl_add_u64 v[190:191], v[0:1], 0, v[26:27]
	v_lshl_add_u64 v[0:1], s[4:5], 0, v[24:25]
	v_mov_b32_e32 v199, 0
	v_lshl_add_u64 v[188:189], s[96:97], 0, v[20:21]
	v_lshl_add_u64 v[186:187], s[96:97], 0, v[22:23]
	v_lshl_add_u64 v[98:99], v[0:1], 0, v[26:27]
	s_add_u32 s98, s94, 0x12209000
	s_addc_u32 s99, s95, 0
	s_add_u32 s100, s94, 0x11200000
	s_addc_u32 s101, s95, 0

	v_exp_f32_e32 v48, v48
	v_exp_f32_e32 v49, v49
	v_exp_f32_e32 v50, v50
	v_add_f32_e32 v195, v48, v49
	v_exp_f32_e32 v51, v51
	v_add_f32_e32 v195, v50, v195
	v_exp_f32_e32 v52, v52
	v_add_f32_e32 v195, v51, v195
	v_exp_f32_e32 v53, v53
	v_add_f32_e32 v195, v52, v195
	v_exp_f32_e32 v54, v54
	v_add_f32_e32 v195, v53, v195
	v_exp_f32_e32 v55, v55
	v_add_f32_e32 v195, v54, v195
	v_exp_f32_e32 v56, v56
	v_add_f32_e32 v195, v55, v195
	v_exp_f32_e32 v57, v57
	v_add_f32_e32 v195, v56, v195
	v_exp_f32_e32 v58, v58
	v_add_f32_e32 v195, v57, v195
	v_exp_f32_e32 v59, v59
	v_add_f32_e32 v195, v58, v195
	v_exp_f32_e32 v60, v60
	v_add_f32_e32 v195, v59, v195
	s_movk_i32 s93, 0xbf
	v_mov_b32_e32 v0, 0
	v_mov_b32_e32 v1, v199
	v_mov_b32_e32 v2, v199
	v_mov_b32_e32 v3, v199
	v_mov_b32_e32 v4, v199
	v_mov_b32_e32 v5, v199
	v_mov_b32_e32 v6, v199
	v_mov_b32_e32 v7, v199
	v_mov_b32_e32 v8, v199
	v_mov_b32_e32 v9, v199
	v_mov_b32_e32 v10, v199
	v_mov_b32_e32 v11, v199
	v_mov_b32_e32 v12, v199
	v_mov_b32_e32 v13, v199
	v_mov_b32_e32 v14, v199
	v_mov_b32_e32 v15, v199
	v_mov_b32_e32 v16, 0
	v_mov_b32_e32 v17, v199
	v_mov_b32_e32 v18, v199
	v_mov_b32_e32 v19, v199
	v_mov_b32_e32 v20, v199
	v_mov_b32_e32 v21, v199
	v_mov_b32_e32 v22, v199
	v_mov_b32_e32 v23, v199
	v_mov_b32_e32 v24, v199
	v_mov_b32_e32 v25, v199
	v_mov_b32_e32 v26, v199
	v_mov_b32_e32 v27, v199
	v_mov_b32_e32 v28, v199
	v_mov_b32_e32 v29, v199
	v_mov_b32_e32 v30, v199
	v_mov_b32_e32 v31, v199
.LBB0_1039:
	s_waitcnt lgkmcnt(11)
	v_mfma_f32_32x32x16_bf16 v[64:79], v[172:175], v[100:103], 0
	v_exp_f32_e32 v61, v61
	v_add_f32_e32 v195, v60, v195
	v_exp_f32_e32 v62, v62
	v_add_f32_e32 v195, v61, v195
	s_waitcnt lgkmcnt(9)
	v_mfma_f32_32x32x16_bf16 v[80:95], v[180:183], v[100:103], 0
	v_exp_f32_e32 v63, v63
	v_add_f32_e32 v195, v62, v195
	v_add_f32_e32 v195, v63, v195
	v_exp_f32_e32 v32, v32
	v_mfma_f32_32x32x16_bf16 v[64:79], v[152:155], v[104:107], v[64:79]
	v_exp_f32_e32 v33, v33
	v_exp_f32_e32 v34, v34
	v_add_f32_e32 v251, v32, v33
	v_cvt_pk_bf16_f32 v48, v48, v49
	s_waitcnt lgkmcnt(8)
	v_mfma_f32_32x32x16_bf16 v[80:95], v[164:167], v[104:107], v[80:95]
	v_exp_f32_e32 v35, v35
	v_add_f32_e32 v251, v34, v251
	v_exp_f32_e32 v36, v36
	v_add_f32_e32 v251, v35, v251
	v_cvt_pk_bf16_f32 v49, v50, v51
	s_waitcnt lgkmcnt(7)
	v_mfma_f32_32x32x16_bf16 v[64:79], v[156:159], v[108:111], v[64:79]
	v_exp_f32_e32 v37, v37
	v_add_f32_e32 v251, v36, v251
	v_exp_f32_e32 v38, v38
	v_add_f32_e32 v251, v37, v251
	s_mul_i32 s6, s91, 0x3400
	s_add_i32 s7, s6, 0

	v_add_u32_e32 v253, s7, v96
	s_waitcnt vmcnt(1)
	ds_write_b128 v253, v[128:131]
	s_and_saveexec_b64 s[4:5], s[2:3]
	v_add_u32_e32 v253, s7, v185
	ds_write_b128 v253, v[124:127]
	s_or_b64 exec, exec, s[4:5]
	v_lshl_add_u64 v[200:201], s[100:101], 0, v[190:191]

	v_add_u32_e32 v206, 0xc000, v208
	v_lshl_add_u64 v[128:129], s[98:99], 0, v[188:189]
	s_nop 0
	global_load_dwordx4 v[128:131], v[128:129], off
	s_waitcnt vmcnt(1)
	ds_write2_b64 v206, v[132:133], v[134:135] offset1:2

	s_and_saveexec_b64 s[4:5], s[2:3]
	s_cbranch_execz .LatA_h0
	v_lshl_add_u64 v[124:125], s[98:99], 0, v[186:187]
	s_nop 0
	global_load_dwordx4 v[124:127], v[124:125], off
.LatA_h0:
	s_or_b64 exec, exec, s[4:5]
	global_load_dwordx4 v[132:135], v[200:201], off offset:256

	s_waitcnt lgkmcnt(7)
	v_mfma_f32_32x32x16_bf16 v[80:95], v[176:179], v[108:111], v[80:95]
	v_cvt_pk_bf16_f32 v50, v52, v53
	v_exp_f32_e32 v39, v39
	v_add_f32_e32 v251, v38, v251
	v_exp_f32_e32 v40, v40
	v_add_f32_e32 v251, v39, v251
	v_mfma_f32_32x32x16_bf16 v[64:79], v[140:143], v[112:115], v[64:79]
	v_cvt_pk_bf16_f32 v51, v54, v55
	v_exp_f32_e32 v41, v41
	v_add_f32_e32 v251, v40, v251
	v_exp_f32_e32 v42, v42
	s_waitcnt lgkmcnt(6)
	v_mfma_f32_32x32x16_bf16 v[80:95], v[160:163], v[112:115], v[80:95]
	v_add_f32_e32 v251, v41, v251
	v_cvt_pk_bf16_f32 v52, v56, v57
	v_exp_f32_e32 v43, v43
	v_add_f32_e32 v251, v42, v251
	v_exp_f32_e32 v44, v44
	s_waitcnt lgkmcnt(5)
	v_mfma_f32_32x32x16_bf16 v[64:79], v[148:151], v[116:119], v[64:79]
	v_add_f32_e32 v251, v43, v251
	v_cvt_pk_bf16_f32 v53, v58, v59
	v_exp_f32_e32 v45, v45
	v_add_f32_e32 v251, v44, v251
	v_add_u32_e32 v198, v207, v184
	ds_read_b128 v[210:213], v198 offset:44544
	ds_read_b128 v[214:217], v198 offset:39936
	ds_read_b128 v[218:221], v198 offset:39968
	ds_read_b128 v[222:225], v198 offset:44576
	ds_read_b128 v[226:229], v198 offset:40000
	ds_read_b128 v[230:233], v198 offset:44608
	ds_read_b128 v[234:237], v198 offset:40032
	ds_read_b128 v[238:241], v198 offset:44640
	s_waitcnt lgkmcnt(11)
	v_mfma_f32_32x32x16_bf16 v[80:95], v[168:171], v[116:119], v[80:95]
	v_exp_f32_e32 v46, v46
	v_add_f32_e32 v251, v45, v251
	v_cvt_pk_bf16_f32 v54, v60, v61
	v_exp_f32_e32 v47, v47
	v_add_f32_e32 v251, v46, v251
	v_mfma_f32_32x32x16_bf16 v[64:79], v[136:139], v[120:123], v[64:79]
	v_add_f32_e32 v251, v47, v251
	v_cvt_pk_bf16_f32 v55, v62, v63
	v_cvt_pk_bf16_f32 v32, v32, v33
	v_cvt_pk_bf16_f32 v33, v34, v35
	v_cvt_pk_bf16_f32 v34, v36, v37
	v_cvt_pk_bf16_f32 v35, v38, v39
	s_waitcnt lgkmcnt(10)
	v_mfma_f32_32x32x16_bf16 v[80:95], v[144:147], v[120:123], v[80:95]
	v_cvt_pk_bf16_f32 v36, v40, v41
	v_cvt_pk_bf16_f32 v37, v42, v43
	v_cvt_pk_bf16_f32 v38, v44, v45
	v_cvt_pk_bf16_f32 v39, v46, v47
	v_add_f32_e32 v195, v195, v251
	v_add_f32_e32 v199, v199, v195
	s_waitcnt lgkmcnt(0)
	s_barrier

	v_add_u32_e32 v197, s6, v204
	s_setprio 1
	v_mfma_f32_32x32x16_bf16 v[0:15], v[48:51], v[210:213], v[0:15]
	ds_read_b128 v[172:175], v197
	ds_read_b128 v[152:155], v197 offset:32
	v_mfma_f32_32x32x16_bf16 v[0:15], v[52:55], v[222:225], v[0:15]
	ds_read_b128 v[180:183], v197 offset:6656
	ds_read_b128 v[164:167], v197 offset:6688
	v_mfma_f32_32x32x16_bf16 v[0:15], v[32:35], v[230:233], v[0:15]
	ds_read_b128 v[156:159], v197 offset:64
	ds_read_b128 v[140:143], v197 offset:96
	v_exp_f32_e32 v64, v64
	v_exp_f32_e32 v65, v65
	v_exp_f32_e32 v66, v66
	v_mfma_f32_32x32x16_bf16 v[0:15], v[36:39], v[238:241], v[0:15]
	s_setprio 0
	ds_read_b128 v[176:179], v197 offset:6720
	ds_read_b128 v[160:163], v197 offset:6752
	v_add_f32_e32 v195, v64, v65
	v_exp_f32_e32 v67, v67
	v_add_f32_e32 v195, v66, v195
	v_exp_f32_e32 v68, v68
	v_mfma_f32_32x32x16_bf16 v[16:31], v[48:51], v[214:217], v[16:31]
	ds_read_b128 v[148:151], v197 offset:128
	ds_read_b128 v[136:139], v197 offset:160
	v_add_f32_e32 v195, v67, v195
	v_exp_f32_e32 v69, v69
	v_add_f32_e32 v195, v68, v195
	v_exp_f32_e32 v70, v70
	v_add_f32_e32 v195, v69, v195
	v_mfma_f32_32x32x16_bf16 v[16:31], v[52:55], v[218:221], v[16:31]
	ds_read_b128 v[168:171], v197 offset:6784
	ds_read_b128 v[144:147], v197 offset:6816
	v_exp_f32_e32 v71, v71
	v_add_f32_e32 v195, v70, v195
	v_exp_f32_e32 v72, v72
	v_add_f32_e32 v195, v71, v195
	v_mfma_f32_32x32x16_bf16 v[16:31], v[32:35], v[226:229], v[16:31]
	v_exp_f32_e32 v73, v73
	v_add_f32_e32 v195, v72, v195
	v_exp_f32_e32 v74, v74
	v_add_f32_e32 v195, v73, v195
	v_mfma_f32_32x32x16_bf16 v[16:31], v[36:39], v[234:237], v[16:31]
	v_exp_f32_e32 v75, v75
	v_add_f32_e32 v195, v74, v195
	v_exp_f32_e32 v76, v76
	v_add_f32_e32 v195, v75, v195
	s_waitcnt lgkmcnt(11)
	v_mfma_f32_32x32x16_bf16 v[48:63], v[172:175], v[100:103], 0
	v_exp_f32_e32 v77, v77
	v_add_f32_e32 v195, v76, v195
	v_exp_f32_e32 v78, v78
	v_add_f32_e32 v195, v77, v195
	s_waitcnt lgkmcnt(9)
	v_mfma_f32_32x32x16_bf16 v[32:47], v[180:183], v[100:103], 0
	v_exp_f32_e32 v79, v79
	v_add_f32_e32 v195, v78, v195
	v_add_f32_e32 v195, v79, v195
	v_exp_f32_e32 v80, v80
	v_mfma_f32_32x32x16_bf16 v[48:63], v[152:155], v[104:107], v[48:63]
	v_exp_f32_e32 v81, v81
	v_exp_f32_e32 v82, v82
	v_add_f32_e32 v251, v80, v81
	v_cvt_pk_bf16_f32 v64, v64, v65
	s_waitcnt lgkmcnt(8)
	v_mfma_f32_32x32x16_bf16 v[32:47], v[164:167], v[104:107], v[32:47]
	v_exp_f32_e32 v83, v83
	v_add_f32_e32 v251, v82, v251
	v_exp_f32_e32 v84, v84
	v_add_f32_e32 v251, v83, v251
	v_cvt_pk_bf16_f32 v65, v66, v67
	s_waitcnt lgkmcnt(7)
	v_mfma_f32_32x32x16_bf16 v[48:63], v[156:159], v[108:111], v[48:63]
	v_exp_f32_e32 v85, v85
	v_add_f32_e32 v251, v84, v251
	v_exp_f32_e32 v86, v86
	v_add_f32_e32 v251, v85, v251
	s_add_i32 s4, s91, 1
	s_cmp_lg_u32 s91, 2
	s_cselect_b32 s74, s4, 0
	s_mul_i32 s6, s74, 0x3400
	s_add_i32 s7, s6, 0
	s_add_u32 s98, s98, 0x3000
	s_addc_u32 s99, s99, 0

	v_add_u32_e32 v253, s7, v96
	s_waitcnt vmcnt(1)
	ds_write_b128 v253, v[128:131]
	s_and_saveexec_b64 s[4:5], s[2:3]
	v_add_u32_e32 v253, s7, v185
	ds_write_b128 v253, v[124:127]
	s_or_b64 exec, exec, s[4:5]
	v_lshl_add_u64 v[200:201], s[100:101], 0, v[190:191]

	s_waitcnt vmcnt(0)
	ds_write2_b64 v205, v[132:133], v[134:135] offset0:128 offset1:130
	v_lshl_add_u64 v[128:129], s[98:99], 0, v[188:189]
	s_nop 0
	global_load_dwordx4 v[128:131], v[128:129], off

	s_and_saveexec_b64 s[4:5], s[2:3]
	s_cbranch_execz .LatA_h1
	v_lshl_add_u64 v[124:125], s[98:99], 0, v[186:187]
	s_nop 0
	global_load_dwordx4 v[124:127], v[124:125], off
.LatA_h1:
	s_or_b64 exec, exec, s[4:5]
	global_load_dwordx4 v[132:135], v[200:201], off offset:384

	s_sub_u32 s98, s98, 0x3000
	s_subb_u32 s99, s99, 0

	s_waitcnt lgkmcnt(7)
	v_mfma_f32_32x32x16_bf16 v[32:47], v[176:179], v[108:111], v[32:47]
	v_cvt_pk_bf16_f32 v66, v68, v69
	v_exp_f32_e32 v87, v87
	v_add_f32_e32 v251, v86, v251
	v_exp_f32_e32 v88, v88
	v_add_f32_e32 v251, v87, v251
	v_mfma_f32_32x32x16_bf16 v[48:63], v[140:143], v[112:115], v[48:63]
	v_cvt_pk_bf16_f32 v67, v70, v71
	v_exp_f32_e32 v89, v89
	v_add_f32_e32 v251, v88, v251
	v_exp_f32_e32 v90, v90
	s_waitcnt lgkmcnt(6)
	v_mfma_f32_32x32x16_bf16 v[32:47], v[160:163], v[112:115], v[32:47]
	v_add_f32_e32 v251, v89, v251
	v_cvt_pk_bf16_f32 v68, v72, v73
	v_exp_f32_e32 v91, v91
	v_add_f32_e32 v251, v90, v251
	v_exp_f32_e32 v92, v92
	s_waitcnt lgkmcnt(5)
	v_mfma_f32_32x32x16_bf16 v[48:63], v[148:151], v[116:119], v[48:63]
	v_add_f32_e32 v251, v91, v251
	v_cvt_pk_bf16_f32 v69, v74, v75
	v_exp_f32_e32 v93, v93
	v_add_f32_e32 v251, v92, v251
	v_add_u32_e32 v198, v207, v184
	ds_read_b128 v[210:213], v198 offset:53760
	ds_read_b128 v[214:217], v198 offset:49152
	ds_read_b128 v[218:221], v198 offset:49184
	ds_read_b128 v[222:225], v198 offset:53792
	ds_read_b128 v[226:229], v198 offset:49216
	ds_read_b128 v[230:233], v198 offset:53824
	ds_read_b128 v[234:237], v198 offset:49248
	ds_read_b128 v[238:241], v198 offset:53856
	s_waitcnt lgkmcnt(11)
	v_mfma_f32_32x32x16_bf16 v[32:47], v[168:171], v[116:119], v[32:47]
	v_exp_f32_e32 v94, v94
	v_add_f32_e32 v251, v93, v251
	v_cvt_pk_bf16_f32 v70, v76, v77
	v_exp_f32_e32 v95, v95
	v_add_f32_e32 v251, v94, v251
	v_mfma_f32_32x32x16_bf16 v[48:63], v[136:139], v[120:123], v[48:63]
	v_add_f32_e32 v251, v95, v251
	v_cvt_pk_bf16_f32 v71, v78, v79
	v_cvt_pk_bf16_f32 v80, v80, v81
	v_cvt_pk_bf16_f32 v81, v82, v83
	v_cvt_pk_bf16_f32 v82, v84, v85
	v_cvt_pk_bf16_f32 v83, v86, v87
	s_waitcnt lgkmcnt(10)
	v_mfma_f32_32x32x16_bf16 v[32:47], v[144:147], v[120:123], v[32:47]
	v_cvt_pk_bf16_f32 v84, v88, v89
	v_cvt_pk_bf16_f32 v85, v90, v91
	v_cvt_pk_bf16_f32 v86, v92, v93
	v_cvt_pk_bf16_f32 v87, v94, v95
	v_add_f32_e32 v195, v195, v251
	v_add_f32_e32 v199, v199, v195
	s_add_i32 s92, s79, 2
	s_waitcnt lgkmcnt(0)
	s_barrier

	s_cmp_ge_u32 s92, s87
	s_cbranch_scc1 .LatA_yplain

	v_add_u32_e32 v197, s6, v204
	s_setprio 1
	v_mfma_f32_32x32x16_bf16 v[0:15], v[64:67], v[210:213], v[0:15]
	ds_read_b128 v[172:175], v197
	ds_read_b128 v[152:155], v197 offset:32
	v_mfma_f32_32x32x16_bf16 v[0:15], v[68:71], v[222:225], v[0:15]
	ds_read_b128 v[180:183], v197 offset:6656
	ds_read_b128 v[164:167], v197 offset:6688
	v_mfma_f32_32x32x16_bf16 v[0:15], v[80:83], v[230:233], v[0:15]
	ds_read_b128 v[156:159], v197 offset:64
	ds_read_b128 v[140:143], v197 offset:96
	v_exp_f32_e32 v48, v48
	v_exp_f32_e32 v49, v49
	v_exp_f32_e32 v50, v50
	v_mfma_f32_32x32x16_bf16 v[0:15], v[84:87], v[238:241], v[0:15]
	s_setprio 0
	ds_read_b128 v[176:179], v197 offset:6720
	ds_read_b128 v[160:163], v197 offset:6752
	v_add_f32_e32 v195, v48, v49
	v_exp_f32_e32 v51, v51
	v_add_f32_e32 v195, v50, v195
	v_exp_f32_e32 v52, v52
	v_mfma_f32_32x32x16_bf16 v[16:31], v[64:67], v[214:217], v[16:31]
	ds_read_b128 v[148:151], v197 offset:128
	ds_read_b128 v[136:139], v197 offset:160
	v_add_f32_e32 v195, v51, v195
	v_exp_f32_e32 v53, v53
	v_add_f32_e32 v195, v52, v195
	v_exp_f32_e32 v54, v54
	v_add_f32_e32 v195, v53, v195
	v_mfma_f32_32x32x16_bf16 v[16:31], v[68:71], v[218:221], v[16:31]
	ds_read_b128 v[168:171], v197 offset:6784
	ds_read_b128 v[144:147], v197 offset:6816
	v_exp_f32_e32 v55, v55
	v_add_f32_e32 v195, v54, v195
	v_exp_f32_e32 v56, v56
	v_add_f32_e32 v195, v55, v195
	v_mfma_f32_32x32x16_bf16 v[16:31], v[80:83], v[226:229], v[16:31]
	v_exp_f32_e32 v57, v57
	v_add_f32_e32 v195, v56, v195
	v_exp_f32_e32 v58, v58
	v_add_f32_e32 v195, v57, v195
	v_mfma_f32_32x32x16_bf16 v[16:31], v[84:87], v[234:237], v[16:31]
	v_exp_f32_e32 v59, v59
	v_add_f32_e32 v195, v58, v195
	v_exp_f32_e32 v60, v60
	v_add_f32_e32 v195, v59, v195
	s_branch .LatA_ctl

.LBB0_1103:
	s_or_b64 exec, exec, s[4:5]
	v_and_b32_e32 v2, 0x60, v190
	s_movk_i32 s4, 0x90
	v_lshlrev_b32_e32 v1, 3, v24
	v_mad_u32_u24 v208, v207, s4, 0
	v_mad_u64_u32 v[2:3], s[4:5], v20, s4, v[2:3]
	v_and_or_b32 v1, v1, 8, v2
	v_lshlrev_b32_e32 v2, 6, v207
	v_add_u32_e32 v210, 0, v1
	v_add3_u32 v209, v208, v2, v184
	v_add_u32_e32 v0, 0, v0
	v_add_u32_e32 v211, 0x9800, v210
	s_waitcnt vmcnt(3)
	ds_write_b128 v0, v[4:7] offset:13312
	s_waitcnt vmcnt(2)
	ds_write2_b64 v211, v[8:9], v[10:11] offset0:128 offset1:130
	s_waitcnt lgkmcnt(0)
	s_barrier
	ds_read_b128 v[0:3], v209
	ds_read_b128 v[4:7], v209 offset:32
	ds_read_b128 v[8:11], v209 offset:6656
	ds_read_b128 v[12:15], v209 offset:6688
	ds_read_b128 v[16:19], v209 offset:64
	ds_read_b128 v[20:23], v209 offset:96
	ds_read_b128 v[24:27], v209 offset:6720
	ds_read_b128 v[28:31], v209 offset:6752
	ds_read_b128 v[64:67], v209 offset:128
	ds_read_b128 v[68:71], v209 offset:160
	ds_read_b128 v[72:75], v209 offset:6784
	ds_read_b128 v[76:79], v209 offset:6816
	s_mov_b32 s90, 2
	s_lshl_b32 s69, s68, 2
	s_mov_b32 s40, 0
	s_cmp_eq_u32 s68, 0
	s_waitcnt lgkmcnt(11)
	v_mfma_f32_32x32x16_bf16 v[48:63], v[0:3], v[100:103], 0
	s_waitcnt lgkmcnt(9)
	v_mfma_f32_32x32x16_bf16 v[32:47], v[8:11], v[100:103], 0
	v_mfma_f32_32x32x16_bf16 v[48:63], v[4:7], v[104:107], v[48:63]
	s_waitcnt lgkmcnt(8)
	v_mfma_f32_32x32x16_bf16 v[32:47], v[12:15], v[104:107], v[32:47]
	s_waitcnt lgkmcnt(7)
	v_mfma_f32_32x32x16_bf16 v[48:63], v[16:19], v[108:111], v[48:63]
	s_waitcnt lgkmcnt(5)
	v_mfma_f32_32x32x16_bf16 v[32:47], v[24:27], v[108:111], v[32:47]
	v_mfma_f32_32x32x16_bf16 v[48:63], v[20:23], v[112:115], v[48:63]
	s_waitcnt lgkmcnt(4)
	v_mfma_f32_32x32x16_bf16 v[32:47], v[28:31], v[112:115], v[32:47]
	s_waitcnt lgkmcnt(3)
	v_mfma_f32_32x32x16_bf16 v[48:63], v[64:67], v[116:119], v[48:63]
	s_waitcnt lgkmcnt(1)
	v_mfma_f32_32x32x16_bf16 v[32:47], v[72:75], v[116:119], v[32:47]
	v_mfma_f32_32x32x16_bf16 v[48:63], v[68:71], v[120:123], v[48:63]
	s_waitcnt lgkmcnt(0)
	v_mfma_f32_32x32x16_bf16 v[32:47], v[76:79], v[120:123], v[32:47]
	s_cbranch_scc1 .LBB0_1114
	ds_read_b128 v[172:175], v209 offset:13312
	ds_read_b128 v[152:155], v209 offset:13344
	ds_read_b128 v[180:183], v209 offset:19968
	ds_read_b128 v[164:167], v209 offset:20000
	ds_read_b128 v[156:159], v209 offset:13376
	ds_read_b128 v[140:143], v209 offset:13408
	ds_read_b128 v[176:179], v209 offset:20032
	ds_read_b128 v[160:163], v209 offset:20064
	ds_read_b128 v[148:151], v209 offset:13440
	ds_read_b128 v[136:139], v209 offset:13472
	ds_read_b128 v[168:171], v209 offset:20096
	ds_read_b128 v[144:147], v209 offset:20128
	v_lshl_add_u64 v[0:1], s[60:61], 0, v[192:193]
	v_mov_b32_e32 v191, v97
	v_mov_b32_e32 v198, 0
	v_lshl_add_u64 v[98:99], s[96:97], 0, v[186:187]
	v_lshl_add_u64 v[202:203], s[96:97], 0, v[188:189]
	v_lshl_add_u64 v[204:205], v[0:1], 0, v[190:191]
	s_add_u32 s98, s94, 0x12209000
	s_addc_u32 s99, s95, 0
	s_add_u32 s100, s94, 0x11200000
	s_addc_u32 s101, s95, 0

	v_exp_f32_e32 v48, v48
	v_exp_f32_e32 v49, v49
	v_exp_f32_e32 v50, v50
	v_add_f32_e32 v195, v48, v49
	v_exp_f32_e32 v51, v51
	v_add_f32_e32 v195, v50, v195
	v_exp_f32_e32 v52, v52
	v_add_f32_e32 v195, v51, v195
	v_exp_f32_e32 v53, v53
	v_add_f32_e32 v195, v52, v195
	v_exp_f32_e32 v54, v54
	v_add_f32_e32 v195, v53, v195
	v_exp_f32_e32 v55, v55
	v_add_f32_e32 v195, v54, v195
	v_exp_f32_e32 v56, v56
	v_add_f32_e32 v195, v55, v195
	v_exp_f32_e32 v57, v57
	v_add_f32_e32 v195, v56, v195
	v_exp_f32_e32 v58, v58
	v_add_f32_e32 v195, v57, v195
	v_exp_f32_e32 v59, v59
	v_add_f32_e32 v195, v58, v195
	v_exp_f32_e32 v60, v60
	v_add_f32_e32 v195, v59, v195
	v_mov_b32_e32 v0, 0
	v_mov_b32_e32 v1, v198
	v_mov_b32_e32 v2, v198
	v_mov_b32_e32 v3, v198
	v_mov_b32_e32 v4, v198
	v_mov_b32_e32 v5, v198
	v_mov_b32_e32 v6, v198
	v_mov_b32_e32 v7, v198
	v_mov_b32_e32 v8, v198
	v_mov_b32_e32 v9, v198
	v_mov_b32_e32 v10, v198
	v_mov_b32_e32 v11, v198
	v_mov_b32_e32 v12, v198
	v_mov_b32_e32 v13, v198
	v_mov_b32_e32 v14, v198
	v_mov_b32_e32 v15, v198
	v_mov_b32_e32 v16, 0
	v_mov_b32_e32 v17, v198
	v_mov_b32_e32 v18, v198
	v_mov_b32_e32 v19, v198
	v_mov_b32_e32 v20, v198
	v_mov_b32_e32 v21, v198
	v_mov_b32_e32 v22, v198
	v_mov_b32_e32 v23, v198
	v_mov_b32_e32 v24, v198
	v_mov_b32_e32 v25, v198
	v_mov_b32_e32 v26, v198
	v_mov_b32_e32 v27, v198
	v_mov_b32_e32 v28, v198
	v_mov_b32_e32 v29, v198
	v_mov_b32_e32 v30, v198
	v_mov_b32_e32 v31, v198
	s_mov_b32 s41, 0x2c000
	s_branch .LBB0_1106
.LBB0_1106:
	s_waitcnt lgkmcnt(11)
	v_mfma_f32_32x32x16_bf16 v[64:79], v[172:175], v[100:103], 0
	v_exp_f32_e32 v61, v61
	v_add_f32_e32 v195, v60, v195
	v_exp_f32_e32 v62, v62
	v_add_f32_e32 v195, v61, v195
	s_waitcnt lgkmcnt(9)
	v_mfma_f32_32x32x16_bf16 v[80:95], v[180:183], v[100:103], 0
	v_exp_f32_e32 v63, v63
	v_add_f32_e32 v195, v62, v195
	v_add_f32_e32 v195, v63, v195
	v_exp_f32_e32 v32, v32
	v_mfma_f32_32x32x16_bf16 v[64:79], v[152:155], v[104:107], v[64:79]
	v_exp_f32_e32 v33, v33
	v_exp_f32_e32 v34, v34
	v_add_f32_e32 v251, v32, v33
	v_cvt_pk_bf16_f32 v48, v48, v49
	s_waitcnt lgkmcnt(8)
	v_mfma_f32_32x32x16_bf16 v[80:95], v[164:167], v[104:107], v[80:95]
	v_exp_f32_e32 v35, v35
	v_add_f32_e32 v251, v34, v251
	v_exp_f32_e32 v36, v36
	v_add_f32_e32 v251, v35, v251
	v_cvt_pk_bf16_f32 v49, v50, v51
	s_waitcnt lgkmcnt(7)
	v_mfma_f32_32x32x16_bf16 v[64:79], v[156:159], v[108:111], v[64:79]
	v_exp_f32_e32 v37, v37
	v_add_f32_e32 v251, v36, v251
	v_exp_f32_e32 v38, v38
	v_add_f32_e32 v251, v37, v251
	s_mul_i32 s6, s90, 0x3400
	s_add_i32 s7, s6, 0

	v_add_u32_e32 v253, s7, v96
	s_waitcnt vmcnt(1)
	ds_write_b128 v253, v[128:131]
	s_and_saveexec_b64 s[4:5], s[2:3]
	v_add_u32_e32 v253, s7, v185
	ds_write_b128 v253, v[124:127]
	s_or_b64 exec, exec, s[4:5]
	v_lshl_add_u64 v[200:201], s[100:101], 0, v[204:205]

	v_add_u32_e32 v254, 0xc000, v210
	v_lshl_add_u64 v[128:129], s[98:99], 0, v[98:99]
	s_nop 0
	global_load_dwordx4 v[128:131], v[128:129], off
	s_waitcnt vmcnt(1)
	ds_write2_b64 v254, v[132:133], v[134:135] offset1:2

	s_and_saveexec_b64 s[4:5], s[2:3]
	s_cbranch_execz .LatB_h0
	v_lshl_add_u64 v[124:125], s[98:99], 0, v[202:203]
	s_nop 0
	global_load_dwordx4 v[124:127], v[124:125], off
.LatB_h0:
	s_or_b64 exec, exec, s[4:5]
	global_load_dwordx4 v[132:135], v[200:201], off offset:256

	s_waitcnt lgkmcnt(7)
	v_mfma_f32_32x32x16_bf16 v[80:95], v[176:179], v[108:111], v[80:95]
	v_cvt_pk_bf16_f32 v50, v52, v53
	v_exp_f32_e32 v39, v39
	v_add_f32_e32 v251, v38, v251
	v_exp_f32_e32 v40, v40
	v_add_f32_e32 v251, v39, v251
	v_mfma_f32_32x32x16_bf16 v[64:79], v[140:143], v[112:115], v[64:79]
	v_cvt_pk_bf16_f32 v51, v54, v55
	v_exp_f32_e32 v41, v41
	v_add_f32_e32 v251, v40, v251
	v_exp_f32_e32 v42, v42
	s_waitcnt lgkmcnt(6)
	v_mfma_f32_32x32x16_bf16 v[80:95], v[160:163], v[112:115], v[80:95]
	v_add_f32_e32 v251, v41, v251
	v_cvt_pk_bf16_f32 v52, v56, v57
	v_exp_f32_e32 v43, v43
	v_add_f32_e32 v251, v42, v251
	v_exp_f32_e32 v44, v44
	s_waitcnt lgkmcnt(5)
	v_mfma_f32_32x32x16_bf16 v[64:79], v[148:151], v[116:119], v[64:79]
	v_add_f32_e32 v251, v43, v251
	v_cvt_pk_bf16_f32 v53, v58, v59
	v_exp_f32_e32 v45, v45
	v_add_f32_e32 v251, v44, v251
	v_add_u32_e32 v196, v208, v184
	ds_read_b128 v[212:215], v196 offset:44544
	ds_read_b128 v[216:219], v196 offset:39936
	ds_read_b128 v[220:223], v196 offset:39968
	ds_read_b128 v[224:227], v196 offset:44576
	ds_read_b128 v[228:231], v196 offset:40000
	ds_read_b128 v[232:235], v196 offset:44608
	ds_read_b128 v[236:239], v196 offset:40032
	ds_read_b128 v[240:243], v196 offset:44640
	s_waitcnt lgkmcnt(11)
	v_mfma_f32_32x32x16_bf16 v[80:95], v[168:171], v[116:119], v[80:95]
	v_exp_f32_e32 v46, v46
	v_add_f32_e32 v251, v45, v251
	v_cvt_pk_bf16_f32 v54, v60, v61
	v_exp_f32_e32 v47, v47
	v_add_f32_e32 v251, v46, v251
	v_mfma_f32_32x32x16_bf16 v[64:79], v[136:139], v[120:123], v[64:79]
	v_add_f32_e32 v251, v47, v251
	v_cvt_pk_bf16_f32 v55, v62, v63
	v_cvt_pk_bf16_f32 v32, v32, v33
	v_cvt_pk_bf16_f32 v33, v34, v35
	v_cvt_pk_bf16_f32 v34, v36, v37
	v_cvt_pk_bf16_f32 v35, v38, v39
	s_waitcnt lgkmcnt(10)
	v_mfma_f32_32x32x16_bf16 v[80:95], v[144:147], v[120:123], v[80:95]
	v_cvt_pk_bf16_f32 v36, v40, v41
	v_cvt_pk_bf16_f32 v37, v42, v43
	v_cvt_pk_bf16_f32 v38, v44, v45
	v_cvt_pk_bf16_f32 v39, v46, v47
	v_add_f32_e32 v195, v195, v251
	v_add_f32_e32 v198, v198, v195
	s_waitcnt lgkmcnt(0)
	s_barrier

	v_add_u32_e32 v197, s6, v209
	s_setprio 1
	v_mfma_f32_32x32x16_bf16 v[0:15], v[48:51], v[212:215], v[0:15]
	ds_read_b128 v[172:175], v197
	ds_read_b128 v[152:155], v197 offset:32
	v_mfma_f32_32x32x16_bf16 v[0:15], v[52:55], v[224:227], v[0:15]
	ds_read_b128 v[180:183], v197 offset:6656
	ds_read_b128 v[164:167], v197 offset:6688
	v_mfma_f32_32x32x16_bf16 v[0:15], v[32:35], v[232:235], v[0:15]
	ds_read_b128 v[156:159], v197 offset:64
	ds_read_b128 v[140:143], v197 offset:96
	v_exp_f32_e32 v64, v64
	v_exp_f32_e32 v65, v65
	v_exp_f32_e32 v66, v66
	v_mfma_f32_32x32x16_bf16 v[0:15], v[36:39], v[240:243], v[0:15]
	s_setprio 0
	ds_read_b128 v[176:179], v197 offset:6720
	ds_read_b128 v[160:163], v197 offset:6752
	v_add_f32_e32 v195, v64, v65
	v_exp_f32_e32 v67, v67
	v_add_f32_e32 v195, v66, v195
	v_exp_f32_e32 v68, v68
	v_mfma_f32_32x32x16_bf16 v[16:31], v[48:51], v[216:219], v[16:31]
	ds_read_b128 v[148:151], v197 offset:128
	ds_read_b128 v[136:139], v197 offset:160
	v_add_f32_e32 v195, v67, v195
	v_exp_f32_e32 v69, v69
	v_add_f32_e32 v195, v68, v195
	v_exp_f32_e32 v70, v70
	v_add_f32_e32 v195, v69, v195
	v_mfma_f32_32x32x16_bf16 v[16:31], v[52:55], v[220:223], v[16:31]
	ds_read_b128 v[168:171], v197 offset:6784
	ds_read_b128 v[144:147], v197 offset:6816
	v_exp_f32_e32 v71, v71
	v_add_f32_e32 v195, v70, v195
	v_exp_f32_e32 v72, v72
	v_add_f32_e32 v195, v71, v195
	v_mfma_f32_32x32x16_bf16 v[16:31], v[32:35], v[228:231], v[16:31]
	v_exp_f32_e32 v73, v73
	v_add_f32_e32 v195, v72, v195
	v_exp_f32_e32 v74, v74
	v_add_f32_e32 v195, v73, v195
	v_mfma_f32_32x32x16_bf16 v[16:31], v[36:39], v[236:239], v[16:31]
	v_exp_f32_e32 v75, v75
	v_add_f32_e32 v195, v74, v195
	v_exp_f32_e32 v76, v76
	v_add_f32_e32 v195, v75, v195
	s_waitcnt lgkmcnt(11)
	v_mfma_f32_32x32x16_bf16 v[48:63], v[172:175], v[100:103], 0
	v_exp_f32_e32 v77, v77
	v_add_f32_e32 v195, v76, v195
	v_exp_f32_e32 v78, v78
	v_add_f32_e32 v195, v77, v195
	s_waitcnt lgkmcnt(9)
	v_mfma_f32_32x32x16_bf16 v[32:47], v[180:183], v[100:103], 0
	v_exp_f32_e32 v79, v79
	v_add_f32_e32 v195, v78, v195
	v_add_f32_e32 v195, v79, v195
	v_exp_f32_e32 v80, v80
	v_mfma_f32_32x32x16_bf16 v[48:63], v[152:155], v[104:107], v[48:63]
	v_exp_f32_e32 v81, v81
	v_exp_f32_e32 v82, v82
	v_add_f32_e32 v251, v80, v81
	v_cvt_pk_bf16_f32 v64, v64, v65
	s_waitcnt lgkmcnt(8)
	v_mfma_f32_32x32x16_bf16 v[32:47], v[164:167], v[104:107], v[32:47]
	v_exp_f32_e32 v83, v83
	v_add_f32_e32 v251, v82, v251
	v_exp_f32_e32 v84, v84
	v_add_f32_e32 v251, v83, v251
	v_cvt_pk_bf16_f32 v65, v66, v67
	s_waitcnt lgkmcnt(7)
	v_mfma_f32_32x32x16_bf16 v[48:63], v[156:159], v[108:111], v[48:63]
	v_exp_f32_e32 v85, v85
	v_add_f32_e32 v251, v84, v251
	v_exp_f32_e32 v86, v86
	v_add_f32_e32 v251, v85, v251
	s_add_i32 s4, s90, 1
	s_cmp_lg_u32 s90, 2
	s_cselect_b32 s68, s4, 0
	s_mul_i32 s6, s68, 0x3400
	s_add_i32 s7, s6, 0
	s_add_u32 s98, s98, 0x3000
	s_addc_u32 s99, s99, 0

	v_add_u32_e32 v253, s7, v96
	s_waitcnt vmcnt(1)
	ds_write_b128 v253, v[128:131]
	s_and_saveexec_b64 s[4:5], s[2:3]
	v_add_u32_e32 v253, s7, v185
	ds_write_b128 v253, v[124:127]
	s_or_b64 exec, exec, s[4:5]
	v_lshl_add_u64 v[200:201], s[100:101], 0, v[204:205]

	s_waitcnt vmcnt(0)
	ds_write2_b64 v211, v[132:133], v[134:135] offset0:128 offset1:130
	v_lshl_add_u64 v[128:129], s[98:99], 0, v[98:99]
	s_nop 0
	global_load_dwordx4 v[128:131], v[128:129], off

	s_and_saveexec_b64 s[4:5], s[2:3]
	s_cbranch_execz .LatB_h1
	v_lshl_add_u64 v[124:125], s[98:99], 0, v[202:203]
	s_nop 0
	global_load_dwordx4 v[124:127], v[124:125], off
.LatB_h1:
	s_or_b64 exec, exec, s[4:5]
	global_load_dwordx4 v[132:135], v[200:201], off offset:384

	s_sub_u32 s98, s98, 0x3000
	s_subb_u32 s99, s99, 0

	s_waitcnt lgkmcnt(7)
	v_mfma_f32_32x32x16_bf16 v[32:47], v[176:179], v[108:111], v[32:47]
	v_cvt_pk_bf16_f32 v66, v68, v69
	v_exp_f32_e32 v87, v87
	v_add_f32_e32 v251, v86, v251
	v_exp_f32_e32 v88, v88
	v_add_f32_e32 v251, v87, v251
	v_mfma_f32_32x32x16_bf16 v[48:63], v[140:143], v[112:115], v[48:63]
	v_cvt_pk_bf16_f32 v67, v70, v71
	v_exp_f32_e32 v89, v89
	v_add_f32_e32 v251, v88, v251
	v_exp_f32_e32 v90, v90
	s_waitcnt lgkmcnt(6)
	v_mfma_f32_32x32x16_bf16 v[32:47], v[160:163], v[112:115], v[32:47]
	v_add_f32_e32 v251, v89, v251
	v_cvt_pk_bf16_f32 v68, v72, v73
	v_exp_f32_e32 v91, v91
	v_add_f32_e32 v251, v90, v251
	v_exp_f32_e32 v92, v92
	s_waitcnt lgkmcnt(5)
	v_mfma_f32_32x32x16_bf16 v[48:63], v[148:151], v[116:119], v[48:63]
	v_add_f32_e32 v251, v91, v251
	v_cvt_pk_bf16_f32 v69, v74, v75
	v_exp_f32_e32 v93, v93
	v_add_f32_e32 v251, v92, v251
	v_add_u32_e32 v196, v208, v184
	ds_read_b128 v[212:215], v196 offset:53760
	ds_read_b128 v[216:219], v196 offset:49152
	ds_read_b128 v[220:223], v196 offset:49184
	ds_read_b128 v[224:227], v196 offset:53792
	ds_read_b128 v[228:231], v196 offset:49216
	ds_read_b128 v[232:235], v196 offset:53824
	ds_read_b128 v[236:239], v196 offset:49248
	ds_read_b128 v[240:243], v196 offset:53856
	s_waitcnt lgkmcnt(11)
	v_mfma_f32_32x32x16_bf16 v[32:47], v[168:171], v[116:119], v[32:47]
	v_exp_f32_e32 v94, v94
	v_add_f32_e32 v251, v93, v251
	v_cvt_pk_bf16_f32 v70, v76, v77
	v_exp_f32_e32 v95, v95
	v_add_f32_e32 v251, v94, v251
	v_mfma_f32_32x32x16_bf16 v[48:63], v[136:139], v[120:123], v[48:63]
	v_add_f32_e32 v251, v95, v251
	v_cvt_pk_bf16_f32 v71, v78, v79
	v_cvt_pk_bf16_f32 v80, v80, v81
	v_cvt_pk_bf16_f32 v81, v82, v83
	v_cvt_pk_bf16_f32 v82, v84, v85
	v_cvt_pk_bf16_f32 v83, v86, v87
	s_waitcnt lgkmcnt(10)
	v_mfma_f32_32x32x16_bf16 v[32:47], v[144:147], v[120:123], v[32:47]
	v_cvt_pk_bf16_f32 v84, v88, v89
	v_cvt_pk_bf16_f32 v85, v90, v91
	v_cvt_pk_bf16_f32 v86, v92, v93
	v_cvt_pk_bf16_f32 v87, v94, v95
	v_add_f32_e32 v195, v195, v251
	v_add_f32_e32 v198, v198, v195
	s_add_i32 s40, s40, 2
	s_waitcnt lgkmcnt(0)
	s_barrier

	s_cmp_ge_u32 s40, s69
	s_cbranch_scc1 .LatB_yplain

	v_add_u32_e32 v197, s6, v209
	s_setprio 1
	v_mfma_f32_32x32x16_bf16 v[0:15], v[64:67], v[212:215], v[0:15]
	ds_read_b128 v[172:175], v197
	ds_read_b128 v[152:155], v197 offset:32
	v_mfma_f32_32x32x16_bf16 v[0:15], v[68:71], v[224:227], v[0:15]
	ds_read_b128 v[180:183], v197 offset:6656
	ds_read_b128 v[164:167], v197 offset:6688
	v_mfma_f32_32x32x16_bf16 v[0:15], v[80:83], v[232:235], v[0:15]
	ds_read_b128 v[156:159], v197 offset:64
	ds_read_b128 v[140:143], v197 offset:96
	v_exp_f32_e32 v48, v48
	v_exp_f32_e32 v49, v49
	v_exp_f32_e32 v50, v50
	v_mfma_f32_32x32x16_bf16 v[0:15], v[84:87], v[240:243], v[0:15]
	s_setprio 0
	ds_read_b128 v[176:179], v197 offset:6720
	ds_read_b128 v[160:163], v197 offset:6752
	v_add_f32_e32 v195, v48, v49
	v_exp_f32_e32 v51, v51
	v_add_f32_e32 v195, v50, v195
	v_exp_f32_e32 v52, v52
	v_mfma_f32_32x32x16_bf16 v[16:31], v[64:67], v[216:219], v[16:31]
	ds_read_b128 v[148:151], v197 offset:128
	ds_read_b128 v[136:139], v197 offset:160
	v_add_f32_e32 v195, v51, v195
	v_exp_f32_e32 v53, v53
	v_add_f32_e32 v195, v52, v195
	v_exp_f32_e32 v54, v54
	v_add_f32_e32 v195, v53, v195
	v_mfma_f32_32x32x16_bf16 v[16:31], v[68:71], v[220:223], v[16:31]
	ds_read_b128 v[168:171], v197 offset:6784
	ds_read_b128 v[144:147], v197 offset:6816
	v_exp_f32_e32 v55, v55
	v_add_f32_e32 v195, v54, v195
	v_exp_f32_e32 v56, v56
	v_add_f32_e32 v195, v55, v195
	v_mfma_f32_32x32x16_bf16 v[16:31], v[80:83], v[228:231], v[16:31]
	v_exp_f32_e32 v57, v57
	v_add_f32_e32 v195, v56, v195
	v_exp_f32_e32 v58, v58
	v_add_f32_e32 v195, v57, v195
	v_mfma_f32_32x32x16_bf16 v[16:31], v[84:87], v[236:239], v[16:31]
	v_exp_f32_e32 v59, v59
	v_add_f32_e32 v195, v58, v195
	v_exp_f32_e32 v60, v60
	v_add_f32_e32 v195, v59, v195
	s_branch .LatB_ctl
